# M13 + attention unit prologue: q head-gain loads issued together instead of one round trip per pair
# baseline (speedup 1.0000x reference)
.Lattn_pro_s:
	global_load_dwordx4 v[50:53], v114, s[44:45] offset:64
	global_load_dwordx4 v[54:57], v114, s[44:45] offset:80
	global_load_dwordx4 v[192:195], v114, s[44:45] offset:128
	global_load_dwordx4 v[196:199], v114, s[44:45] offset:144
	global_load_dwordx4 v[200:203], v114, s[44:45] offset:192
	global_load_dwordx4 v[204:207], v114, s[44:45] offset:208
	global_load_dwordx4 v[208:211], v114, s[44:45] offset:256
	global_load_dwordx4 v[212:215], v114, s[44:45] offset:272
	global_load_dwordx4 v[216:219], v114, s[44:45] offset:320
	global_load_dwordx4 v[220:223], v114, s[44:45] offset:336
	global_load_dwordx4 v[230:233], v114, s[44:45] offset:384
	global_load_dwordx4 v[236:239], v114, s[44:45] offset:400
	global_load_dwordx4 v[240:243], v114, s[44:45] offset:448
	global_load_dwordx4 v[244:247], v114, s[44:45] offset:464
	v_mul_f32_e32 v2, v48, v84
	v_mul_f32_e32 v3, v48, v85
	v_mul_f32_e32 v6, v48, v94
	v_mul_f32_e32 v7, v48, v95
	v_mul_f32_e32 v14, v48, v96
	v_mul_f32_e32 v15, v48, v97
	v_mul_f32_e32 v24, v48, v98
	v_mul_f32_e32 v25, v48, v99
	v_pk_mul_f32 v[12:13], v[48:49], v[12:13] op_sel_hi:[0,1]
	v_pk_mul_f32 v[8:9], v[48:49], v[8:9] op_sel_hi:[0,1]
	v_pk_mul_f32 v[4:5], v[48:49], v[4:5] op_sel_hi:[0,1]
	s_waitcnt vmcnt(13)
	v_mul_f32_e32 v2, v50, v2
	v_mul_f32_e32 v3, v51, v3
	v_cvt_pk_bf16_f32 v120, v2, v3
	v_mul_f32_e32 v2, v48, v86
	v_mul_f32_e32 v3, v48, v87
	v_mul_f32_e32 v2, v52, v2
	v_mul_f32_e32 v3, v53, v3
	v_cvt_pk_bf16_f32 v121, v2, v3
	v_mul_f32_e32 v2, v48, v88
	v_mul_f32_e32 v3, v48, v89
	s_waitcnt vmcnt(12)
	v_mul_f32_e32 v2, v54, v2
	v_mul_f32_e32 v3, v55, v3
	v_cvt_pk_bf16_f32 v122, v2, v3
	v_mul_f32_e32 v2, v48, v90
	v_mul_f32_e32 v3, v48, v91
	v_mul_f32_e32 v2, v56, v2
	v_mul_f32_e32 v3, v57, v3
	v_cvt_pk_bf16_f32 v123, v2, v3
	v_mul_f32_e32 v2, v48, v92
	v_mul_f32_e32 v3, v48, v93
	s_waitcnt vmcnt(11)
	v_mul_f32_e32 v2, v192, v2
	v_mul_f32_e32 v3, v193, v3
	v_mul_f32_e32 v6, v194, v6
	v_mul_f32_e32 v7, v195, v7
	s_waitcnt vmcnt(10)
	v_mul_f32_e32 v14, v196, v14
	v_mul_f32_e32 v15, v197, v15
	v_mul_f32_e32 v24, v198, v24
	v_mul_f32_e32 v25, v199, v25
	v_cvt_pk_bf16_f32 v124, v2, v3
	v_cvt_pk_bf16_f32 v125, v6, v7
	v_cvt_pk_bf16_f32 v126, v14, v15
	v_cvt_pk_bf16_f32 v127, v24, v25
	v_mul_f32_e32 v2, v48, v100
	v_mul_f32_e32 v3, v48, v101
	v_mul_f32_e32 v6, v48, v102
	v_mul_f32_e32 v7, v48, v103
	v_mul_f32_e32 v14, v48, v104
	v_mul_f32_e32 v15, v48, v105
	v_mul_f32_e32 v24, v48, v106
	v_mul_f32_e32 v25, v48, v107
	s_waitcnt vmcnt(9)
	v_mul_f32_e32 v2, v200, v2
	v_mul_f32_e32 v3, v201, v3
	v_mul_f32_e32 v6, v202, v6
	v_mul_f32_e32 v7, v203, v7
	s_waitcnt vmcnt(8)
	v_mul_f32_e32 v14, v204, v14
	v_mul_f32_e32 v15, v205, v15
	v_mul_f32_e32 v24, v206, v24
	v_mul_f32_e32 v25, v207, v25
	v_cvt_pk_bf16_f32 v128, v2, v3
	v_cvt_pk_bf16_f32 v129, v6, v7
	v_cvt_pk_bf16_f32 v130, v14, v15
	v_cvt_pk_bf16_f32 v131, v24, v25
	v_mul_f32_e32 v2, v48, v108
	v_mul_f32_e32 v3, v48, v109
	v_mul_f32_e32 v6, v48, v110
	v_mul_f32_e32 v7, v48, v31
	v_mul_f32_e32 v14, v48, v111
	v_mul_f32_e32 v15, v48, v112
	v_mul_f32_e32 v24, v48, v113
	v_mul_f32_e32 v25, v48, v33
	v_add_u32_e32 v31, 0x200, v175
	v_add_u32_e32 v33, 0x400, v175
	v_lshlrev_b32_e32 v112, 4, v175
	s_waitcnt vmcnt(7)
	v_mul_f32_e32 v2, v208, v2
	v_mul_f32_e32 v3, v209, v3
	v_mul_f32_e32 v6, v210, v6
	v_mul_f32_e32 v7, v211, v7
	s_waitcnt vmcnt(6)
	v_mul_f32_e32 v14, v212, v14
	v_mul_f32_e32 v15, v213, v15
	v_mul_f32_e32 v24, v214, v24
	v_mul_f32_e32 v25, v215, v25
	v_cvt_pk_bf16_f32 v132, v2, v3
	v_cvt_pk_bf16_f32 v133, v6, v7
	v_cvt_pk_bf16_f32 v134, v14, v15
	v_cvt_pk_bf16_f32 v135, v24, v25
	v_mul_f32_e32 v2, v48, v136
	v_mul_f32_e32 v3, v48, v137
	v_mul_f32_e32 v6, v48, v138
	v_mul_f32_e32 v7, v48, v27
	v_mul_f32_e32 v14, v48, v139
	v_mul_f32_e32 v15, v48, v140
	v_mul_f32_e32 v24, v48, v141
	v_mul_f32_e32 v25, v48, v29
	v_lshrrev_b32_e32 v27, 3, v175
	v_mul_hi_i32 v29, v175, s59
	v_bitop3_b32 v27, v27, v174, 1 bitop3:0x6c
	s_waitcnt vmcnt(5)
	v_mul_f32_e32 v2, v216, v2
	v_mul_f32_e32 v3, v217, v3
	v_mul_f32_e32 v6, v218, v6
	v_mul_f32_e32 v7, v219, v7
	s_waitcnt vmcnt(4)
	v_mul_f32_e32 v14, v220, v14
	v_mul_f32_e32 v15, v221, v15
	v_mul_f32_e32 v24, v222, v24
	v_mul_f32_e32 v25, v223, v25
	v_cvt_pk_bf16_f32 v136, v2, v3
	v_cvt_pk_bf16_f32 v137, v6, v7
	v_cvt_pk_bf16_f32 v138, v14, v15
	v_cvt_pk_bf16_f32 v139, v24, v25
	v_mul_f32_e32 v2, v48, v142
	v_mul_f32_e32 v3, v48, v143
	v_mul_f32_e32 v6, v48, v144
	v_mul_f32_e32 v7, v48, v145
	v_mul_f32_e32 v14, v48, v146
	v_mul_f32_e32 v15, v48, v147
	v_mul_f32_e32 v24, v48, v148
	v_mul_f32_e32 v25, v48, v149
	s_waitcnt vmcnt(3)
	v_mul_f32_e32 v2, v230, v2
	v_mul_f32_e32 v3, v231, v3
	v_mul_f32_e32 v6, v232, v6
	v_mul_f32_e32 v7, v233, v7
	s_waitcnt vmcnt(2)
	v_mul_f32_e32 v14, v236, v14
	v_mul_f32_e32 v15, v237, v15
	v_mul_f32_e32 v24, v238, v24
	v_mul_f32_e32 v25, v239, v25
	v_cvt_pk_bf16_f32 v140, v2, v3
	v_cvt_pk_bf16_f32 v141, v6, v7
	v_cvt_pk_bf16_f32 v142, v14, v15
	v_cvt_pk_bf16_f32 v143, v24, v25
	v_lshlrev_b32_e32 v2, 6, v35
	v_ashrrev_i32_e32 v3, 31, v2
	v_lshl_add_u64 v[2:3], v[2:3], 2, s[0:1]
	v_lshl_add_u64 v[50:51], v[2:3], 0, v[114:115]
	v_mul_f32_e32 v2, v48, v150
	v_mul_f32_e32 v3, v48, v151
	v_mul_f32_e32 v6, v48, v152
	v_mul_f32_e32 v7, v48, v153
	v_mul_f32_e32 v14, v48, v154
	v_mul_f32_e32 v15, v48, v155
	v_mul_f32_e32 v24, v48, v156
	v_mul_f32_e32 v25, v48, v157
	v_lshlrev_b32_e32 v35, 5, v173
	s_cselect_b32 s1, 0, 0
	v_lshl_or_b32 v178, v27, 4, v35
	s_add_i32 s0, s1, 0x14b00
	v_lshl_add_u32 v37, v172, 12, s0
	v_add_u32_e32 v177, v37, v178
	s_cmp_lg_u32 s58, -1
	s_cselect_b32 s0, s58, 0
	v_add_u32_e32 v113, s0, v178
	s_add_u32 s6, s52, 0x50180
	s_addc_u32 s7, s53, 0
	s_add_u32 s8, s52, 0x50000
	s_addc_u32 s9, s53, 0
	s_mov_b32 s0, -1
	s_waitcnt vmcnt(1)
	v_mul_f32_e32 v2, v240, v2
	v_mul_f32_e32 v3, v241, v3
	v_mul_f32_e32 v6, v242, v6
	v_mul_f32_e32 v7, v243, v7
	s_waitcnt vmcnt(0)
	v_mul_f32_e32 v14, v244, v14
	v_mul_f32_e32 v15, v245, v15
	v_mul_f32_e32 v24, v246, v24
	v_mul_f32_e32 v25, v247, v25
	v_cvt_pk_bf16_f32 v144, v2, v3
	v_cvt_pk_bf16_f32 v145, v6, v7
	v_cvt_pk_bf16_f32 v146, v14, v15
	v_cvt_pk_bf16_f32 v147, v24, v25
	global_load_dwordx4 v[52:55], v114, s[44:45] offset:512
	global_load_dwordx4 v[56:59], v114, s[44:45] offset:640
	global_load_dwordx4 v[60:63], v[50:51], off
	global_load_dwordx4 v[64:67], v[50:51], off offset:128
	global_load_dwordx4 v[68:71], v114, s[44:45] offset:528
	global_load_dwordx4 v[72:75], v114, s[44:45] offset:656
	global_load_dwordx4 v[76:79], v[50:51], off offset:16
	global_load_dwordx4 v[80:83], v[50:51], off offset:144
	v_pk_mul_f32 v[2:3], v[48:49], v[22:23] op_sel_hi:[0,1]
	v_pk_mul_f32 v[6:7], v[48:49], v[10:11] op_sel_hi:[0,1]
	v_pk_mul_f32 v[10:11], v[48:49], v[20:21] op_sel_hi:[0,1]
	v_pk_mul_f32 v[14:15], v[48:49], v[16:17] op_sel_hi:[0,1]
	v_pk_mul_f32 v[16:17], v[48:49], v[18:19] op_sel_hi:[0,1]
	v_mov_b32_e32 v49, v115
	s_waitcnt vmcnt(7)
	v_mov_b32_e32 v18, v52
	s_waitcnt vmcnt(6)
	v_mov_b32_e32 v19, v56
	v_mov_b32_e32 v56, v53
	v_mov_b32_e32 v24, v54
	v_mov_b32_e32 v25, v58
	v_mov_b32_e32 v58, v55
	s_waitcnt vmcnt(3)
	v_mov_b32_e32 v54, v68
	s_waitcnt vmcnt(2)
	v_mov_b32_e32 v55, v72
	v_mov_b32_e32 v72, v69
	v_mov_b32_e32 v68, v70
	v_mov_b32_e32 v69, v74
	v_mov_b32_e32 v74, v71
	v_mov_b32_e32 v20, v60
	v_mov_b32_e32 v21, v64
	v_mov_b32_e32 v22, v64
	v_mov_b32_e32 v23, v60
	v_mov_b32_e32 v64, v61
	v_mov_b32_e32 v60, v65
	v_mov_b32_e32 v52, v62
	v_mov_b32_e32 v53, v66
	v_mov_b32_e32 v84, v66
	v_mov_b32_e32 v85, v62
	v_mov_b32_e32 v66, v63
	v_mov_b32_e32 v62, v67
	s_waitcnt vmcnt(1)
	v_mov_b32_e32 v86, v76
	s_waitcnt vmcnt(0)
	v_mov_b32_e32 v87, v80
	v_mov_b32_e32 v88, v80
	v_mov_b32_e32 v89, v76
	v_mov_b32_e32 v80, v77
	v_mov_b32_e32 v76, v81
	v_mov_b32_e32 v90, v78
	v_mov_b32_e32 v91, v82
	v_mov_b32_e32 v92, v82
	v_mov_b32_e32 v93, v78
	v_mov_b32_e32 v82, v79
	v_mov_b32_e32 v78, v83
	v_pk_mul_f32 v[2:3], v[18:19], v[2:3]
	v_pk_mul_f32 v[6:7], v[56:57], v[6:7]
	v_pk_mul_f32 v[10:11], v[24:25], v[10:11]
	v_pk_mul_f32 v[14:15], v[58:59], v[14:15]
	v_pk_mul_f32 v[16:17], v[54:55], v[16:17]
	v_pk_mul_f32 v[12:13], v[72:73], v[12:13]
	v_pk_mul_f32 v[8:9], v[68:69], v[8:9]
	v_pk_mul_f32 v[4:5], v[74:75], v[4:5]
	v_pk_mul_f32 v[18:19], v[20:21], v[2:3]
	v_pk_mul_f32 v[2:3], v[22:23], v[2:3]
	v_pk_mul_f32 v[20:21], v[64:65], v[6:7]
	v_pk_mul_f32 v[6:7], v[60:61], v[6:7]
	v_pk_mul_f32 v[22:23], v[52:53], v[10:11]
	v_pk_mul_f32 v[10:11], v[84:85], v[10:11]
	v_pk_mul_f32 v[24:25], v[66:67], v[14:15]
	v_pk_mul_f32 v[14:15], v[62:63], v[14:15]
	v_pk_mul_f32 v[52:53], v[86:87], v[16:17]
	v_pk_mul_f32 v[16:17], v[88:89], v[16:17]
	v_pk_mul_f32 v[54:55], v[80:81], v[12:13]
	v_pk_mul_f32 v[12:13], v[76:77], v[12:13]
	v_pk_mul_f32 v[56:57], v[90:91], v[8:9]
	v_pk_mul_f32 v[8:9], v[92:93], v[8:9]
	v_pk_mul_f32 v[58:59], v[82:83], v[4:5]
	v_pk_mul_f32 v[4:5], v[78:79], v[4:5]
	v_sub_f32_e32 v18, v18, v19
	v_add_f32_e32 v2, v2, v3
	v_sub_f32_e32 v3, v20, v21
	v_add_f32_e32 v6, v6, v7
	v_sub_f32_e32 v7, v22, v23
	v_add_f32_e32 v10, v10, v11
	v_sub_f32_e32 v11, v24, v25
	v_add_f32_e32 v19, v14, v15
	v_sub_f32_e32 v20, v52, v53
	v_add_f32_e32 v21, v16, v17
	v_sub_f32_e32 v16, v54, v55
	v_add_f32_e32 v12, v12, v13
	v_sub_f32_e32 v13, v56, v57
	v_add_f32_e32 v8, v8, v9
	v_sub_f32_e32 v9, v58, v59
	v_add_f32_e32 v4, v4, v5
	v_cvt_pk_bf16_f32 v14, v18, v3
	v_cvt_pk_bf16_f32 v15, v7, v11
	v_cvt_pk_bf16_f32 v16, v20, v16
	v_cvt_pk_bf16_f32 v17, v13, v9
	v_cvt_pk_bf16_f32 v22, v2, v6
	v_cvt_pk_bf16_f32 v23, v10, v19
	v_cvt_pk_bf16_f32 v24, v21, v12
	v_cvt_pk_bf16_f32 v25, v8, v4
	global_load_dwordx4 v[18:21], v114, s[44:45] offset:576
	global_load_dwordx4 v[10:13], v114, s[44:45] offset:704
	global_load_dwordx4 v[2:5], v[50:51], off offset:64
	global_load_dwordx4 v[6:9], v[50:51], off offset:192
	global_load_dwordx4 v[52:55], v114, s[44:45] offset:592
	global_load_dwordx4 v[56:59], v114, s[44:45] offset:720
	global_load_dwordx4 v[66:69], v[50:51], off offset:80
	global_load_dwordx4 v[70:73], v[50:51], off offset:208
	v_lshrrev_b32_e32 v50, 31, v29
	v_ashrrev_i32_e32 v29, 2, v29
	v_mul_hi_i32 v51, v31, s59
	v_mul_hi_i32 v60, v33, s59
	v_add_u32_e32 v84, v29, v50
	v_lshrrev_b32_e32 v27, 31, v51
	v_ashrrev_i32_e32 v29, 2, v51
	v_lshrrev_b32_e32 v35, 31, v60
	v_ashrrev_i32_e32 v50, 2, v60
	v_add_u32_e32 v85, v29, v27
	v_add_u32_e32 v86, v50, v35
	v_ashrrev_i32_e32 v82, 4, v175
	v_lshlrev_b32_e32 v83, 3, v175
	v_mul_lo_u32 v51, v84, 24
	v_mul_lo_u32 v29, v85, 24
	v_mul_lo_u32 v50, v86, 24
	v_and_b32_e32 v76, 0x78, v83
	v_mul_lo_u32 v77, v82, s57
	v_mul_lo_u32 v37, v84, s57
	v_sub_u32_e32 v87, v175, v51
	v_mul_lo_u32 v27, v85, s57
	v_mul_lo_u32 v35, v86, s57
	v_sub_u32_e32 v88, v31, v29
	v_sub_u32_e32 v89, v33, v50
	v_lshl_add_u32 v60, v87, 3, v37
	v_lshl_add_u32 v64, v88, 3, v27
	v_lshl_add_u32 v74, v89, 3, v35
	v_mov_b32_e32 v37, v38
	v_mov_b32_e32 v35, v39
	v_mov_b32_e32 v33, v40
	v_mov_b32_e32 v31, v41
	v_mov_b32_e32 v29, v42
	v_mov_b32_e32 v27, v43
	v_or_b32_e32 v114, v77, v76
	v_pk_mul_f32 v[38:39], v[48:49], v[44:45] op_sel_hi:[0,1]
	v_pk_mul_f32 v[40:41], v[48:49], v[46:47] op_sel_hi:[0,1]
	v_pk_mul_f32 v[36:37], v[48:49], v[36:37] op_sel_hi:[0,1]
	v_pk_mul_f32 v[34:35], v[48:49], v[34:35] op_sel_hi:[0,1]
	v_pk_mul_f32 v[32:33], v[48:49], v[32:33] op_sel_hi:[0,1]
	v_pk_mul_f32 v[30:31], v[48:49], v[30:31] op_sel_hi:[0,1]
	v_pk_mul_f32 v[28:29], v[48:49], v[28:29] op_sel_hi:[0,1]
	v_pk_mul_f32 v[26:27], v[48:49], v[26:27] op_sel_hi:[0,1]
	ds_write_b128 v177, v[14:17]
	ds_write_b128 v177, v[22:25] offset:2048
	v_add_u32_e32 v48, 0x14000, v114
	v_lshlrev_b64 v[102:103], 1, v[48:49]
	v_mov_b32_e32 v61, v115
	v_mov_b32_e32 v65, v115
	v_mov_b32_e32 v75, v115
	v_lshlrev_b64 v[100:101], 1, v[114:115]
	v_lshlrev_b64 v[62:63], 1, v[60:61]
	v_lshlrev_b64 v[64:65], 1, v[64:65]
	v_lshlrev_b64 v[98:99], 1, v[74:75]
	v_lshl_add_u64 v[14:15], s[52:53], 0, v[100:101]
	v_lshl_add_u64 v[16:17], s[52:53], 0, v[102:103]
	v_lshl_add_u64 v[50:51], s[52:53], 0, v[62:63]
	v_lshl_add_u64 v[60:61], s[52:53], 0, v[64:65]
	v_lshl_add_u64 v[74:75], s[52:53], 0, v[98:99]
	v_and_b32_e32 v114, 63, v175
	v_lshlrev_b32_e32 v160, 3, v114
	s_waitcnt vmcnt(7)
	v_mov_b32_e32 v22, v18
	s_waitcnt vmcnt(6)
	v_mov_b32_e32 v23, v10
	v_mov_b32_e32 v10, v19
	v_mov_b32_e32 v18, v20
	v_mov_b32_e32 v19, v12
	v_mov_b32_e32 v12, v21
	s_waitcnt vmcnt(3)
	v_mov_b32_e32 v20, v52
	s_waitcnt vmcnt(2)
	v_mov_b32_e32 v21, v56
	v_mov_b32_e32 v56, v53
	v_mov_b32_e32 v52, v54
	v_mov_b32_e32 v53, v58
	v_mov_b32_e32 v58, v55
	v_mov_b32_e32 v24, v2
	v_mov_b32_e32 v25, v6
	v_mov_b32_e32 v42, v6
	v_mov_b32_e32 v43, v2
	v_mov_b32_e32 v6, v3
	v_mov_b32_e32 v2, v7
	v_mov_b32_e32 v44, v4
	v_mov_b32_e32 v45, v8
	v_mov_b32_e32 v46, v8
	v_mov_b32_e32 v47, v4
	v_mov_b32_e32 v8, v5
	v_mov_b32_e32 v4, v9
	s_waitcnt vmcnt(1)
	v_mov_b32_e32 v48, v66
	s_waitcnt vmcnt(0)
	v_mov_b32_e32 v49, v70
	v_mov_b32_e32 v76, v70
	v_mov_b32_e32 v77, v66
	v_mov_b32_e32 v70, v67
	v_mov_b32_e32 v66, v71
	v_mov_b32_e32 v78, v68
	v_mov_b32_e32 v79, v72
	v_mov_b32_e32 v80, v72
	v_mov_b32_e32 v81, v68
	v_mov_b32_e32 v72, v69
	v_mov_b32_e32 v68, v73
	v_pk_mul_f32 v[22:23], v[22:23], v[38:39]
	v_pk_mul_f32 v[10:11], v[10:11], v[40:41]
	v_pk_mul_f32 v[18:19], v[18:19], v[36:37]
	v_pk_mul_f32 v[12:13], v[12:13], v[34:35]
	v_pk_mul_f32 v[20:21], v[20:21], v[32:33]
	v_pk_mul_f32 v[30:31], v[56:57], v[30:31]
	v_pk_mul_f32 v[28:29], v[52:53], v[28:29]
	v_pk_mul_f32 v[26:27], v[58:59], v[26:27]
	v_pk_mul_f32 v[24:25], v[24:25], v[22:23]
	v_pk_mul_f32 v[22:23], v[42:43], v[22:23]
	v_pk_mul_f32 v[6:7], v[6:7], v[10:11]
	v_pk_mul_f32 v[2:3], v[2:3], v[10:11]
	v_pk_mul_f32 v[10:11], v[44:45], v[18:19]
	v_pk_mul_f32 v[18:19], v[46:47], v[18:19]
	v_pk_mul_f32 v[8:9], v[8:9], v[12:13]
	v_pk_mul_f32 v[4:5], v[4:5], v[12:13]
	v_pk_mul_f32 v[12:13], v[48:49], v[20:21]
	v_pk_mul_f32 v[20:21], v[76:77], v[20:21]
	v_pk_mul_f32 v[32:33], v[70:71], v[30:31]
	v_pk_mul_f32 v[30:31], v[66:67], v[30:31]
	v_pk_mul_f32 v[34:35], v[78:79], v[28:29]
	v_pk_mul_f32 v[28:29], v[80:81], v[28:29]
	v_pk_mul_f32 v[36:37], v[72:73], v[26:27]
	v_pk_mul_f32 v[26:27], v[68:69], v[26:27]
	v_sub_f32_e32 v24, v24, v25
	v_add_f32_e32 v22, v22, v23
	v_sub_f32_e32 v6, v6, v7
	v_add_f32_e32 v7, v2, v3
	v_sub_f32_e32 v3, v10, v11
	v_add_f32_e32 v10, v18, v19
	v_sub_f32_e32 v8, v8, v9
	v_add_f32_e32 v9, v4, v5
	v_sub_f32_e32 v4, v12, v13
	v_add_f32_e32 v11, v20, v21
	v_sub_f32_e32 v5, v32, v33
	v_add_f32_e32 v12, v30, v31
	v_sub_f32_e32 v13, v34, v35
	v_add_f32_e32 v18, v28, v29
	v_sub_f32_e32 v19, v36, v37
	v_add_f32_e32 v20, v26, v27
	v_cvt_pk_bf16_f32 v2, v24, v6
	v_cvt_pk_bf16_f32 v3, v3, v8
	v_cvt_pk_bf16_f32 v4, v4, v5
	v_cvt_pk_bf16_f32 v5, v13, v19
	v_cvt_pk_bf16_f32 v6, v22, v7
	v_cvt_pk_bf16_f32 v7, v10, v9
	v_cvt_pk_bf16_f32 v8, v11, v12
	v_cvt_pk_bf16_f32 v9, v18, v20
	global_load_dwordx4 v[10:13], v[14:15], off offset:384
	s_nop 0
	global_load_dwordx4 v[14:17], v[16:17], off offset:384
	s_nop 0
	global_load_dwordx4 v[18:21], v[50:51], off
	global_load_dwordx4 v[22:25], v[60:61], off
	global_load_dwordx4 v[26:29], v[74:75], off
	v_and_b32_e32 v30, 0xfffff0, v82
	v_lshlrev_b32_e32 v31, 1, v82
	v_lshrrev_b32_e32 v32, 1, v82
	v_and_b32_e32 v34, 3, v82
	v_add_u32_e32 v35, 32, v82
	v_and_or_b32 v30, v31, 8, v30
	v_and_or_b32 v31, v32, 4, v34
	v_and_b32_e32 v32, 0xfffff0, v35
	v_lshlrev_b32_e32 v34, 1, v35
	v_and_or_b32 v32, v34, 8, v32
	v_bfe_u32 v33, v83, 5, 2
	v_lshrrev_b32_e32 v30, 1, v30
	v_lshrrev_b32_e32 v32, 1, v32
	v_lshrrev_b32_e32 v34, 3, v84
	v_or_b32_e32 v30, v30, v33
	v_or_b32_e32 v32, v32, v33
	v_lshrrev_b32_e32 v33, 1, v87
	v_and_b32_e32 v36, 48, v112
	v_lshlrev_b32_e32 v31, 6, v31
	v_lshrrev_b32_e32 v35, 3, v85
	v_lshrrev_b32_e32 v37, 3, v86
	v_lshlrev_b32_e32 v30, 9, v30
	v_xor_b32_e32 v34, v34, v87
	v_mul_lo_u32 v33, v33, s62
	v_lshrrev_b32_e32 v38, 1, v88
	v_lshrrev_b32_e32 v39, 1, v89
	v_lshlrev_b32_e32 v32, 9, v32
	v_lshlrev_b32_e32 v34, 4, v34
	v_xor_b32_e32 v35, v35, v88
	v_xor_b32_e32 v37, v37, v89
	v_or3_b32 v30, v30, v31, v36
	v_lshl_add_u32 v33, v84, 5, v33
	v_mul_lo_u32 v38, v38, s62
	v_mul_lo_u32 v39, v39, s62
	v_lshlrev_b32_e32 v35, 4, v35
	v_lshlrev_b32_e32 v37, 4, v37
	v_or3_b32 v31, v32, v31, v36
	v_add_u32_e32 v181, 0, v30
	v_and_or_b32 v30, v34, 16, v33
	v_lshl_add_u32 v32, v85, 5, v38
	v_lshl_add_u32 v33, v86, 5, v39
	v_add_u32_e32 v182, 0, v31
	v_and_or_b32 v31, v35, 16, v32
	v_and_or_b32 v32, v37, 16, v33
	ds_write_b128 v177, v[2:5] offset:1024
	ds_write_b128 v177, v[6:9] offset:3072
	v_add_u32_e32 v183, 0, v30
	v_add_u32_e32 v192, 0, v31
	v_add_u32_e32 v193, 0, v32
	s_waitcnt vmcnt(0)
	s_waitcnt vmcnt(4)
	ds_write_b128 v181, v[10:13]
	s_waitcnt vmcnt(3)
	ds_write_b128 v182, v[14:17]
	s_waitcnt vmcnt(2)
	ds_write_b128 v183, v[18:21] offset:32768
	s_waitcnt vmcnt(1)
	ds_write_b128 v192, v[22:25] offset:32768
	s_waitcnt vmcnt(0)
	ds_write_b128 v193, v[26:29] offset:32768
	s_waitcnt lgkmcnt(0)
	s_barrier
	ds_read_b128 v[2:5], v113
	ds_read_b128 v[6:9], v113 offset:1024
	s_waitcnt lgkmcnt(1)
	v_mfma_f32_32x32x16_bf16 v[82:97], v[2:5], v[116:119], 0
	v_lshl_add_u64 v[46:47], s[6:7], 0, v[100:101]
	v_lshl_add_u64 v[48:49], s[6:7], 0, v[102:103]
	v_lshl_add_u64 v[40:41], s[8:9], 0, v[62:63]
	v_lshl_add_u64 v[42:43], s[8:9], 0, v[64:65]
	v_lshl_add_u64 v[44:45], s[8:9], 0, v[98:99]
	v_and_b32_e32 v112, 0xc0, v112
	v_and_or_b32 v112, v160, 24, v112
	s_waitcnt lgkmcnt(0)
	v_mfma_f32_32x32x16_bf16 v[66:81], v[6:9], v[116:119], 0
	ds_read_b128 v[2:5], v113 offset:2080
	ds_read_b128 v[6:9], v113 offset:3104
	v_readlane_b32 s8, v254, 60
	v_readlane_b32 s12, v255, 0
	v_readlane_b32 s13, v255, 1
	v_mov_b32_e32 v18, 0
	v_mov_b32_e32 v34, 0
	v_mov_b32_e32 v50, 0
	s_waitcnt lgkmcnt(1)
	v_mfma_f32_32x32x16_bf16 v[82:97], v[2:5], v[120:123], v[82:97]
	v_mov_b32_e32 v19, v180
	v_mov_b32_e32 v35, v180
	v_mov_b32_e32 v51, v180
	v_mov_b32_e32 v60, v180
	v_mov_b32_e32 v61, v180
	v_readlane_b32 s9, v254, 61
	v_readlane_b32 s10, v254, 62
	s_waitcnt lgkmcnt(0)
	v_mfma_f32_32x32x16_bf16 v[66:81], v[6:9], v[120:123], v[66:81]
	ds_read_b128 v[2:5], v113 offset:4160
	ds_read_b128 v[6:9], v113 offset:5184
	ds_read_b128 v[10:13], v113 offset:6240
	ds_read_b128 v[14:17], v113 offset:7264
	ds_read_b128 v[20:23], v113 offset:8320
	ds_read_b128 v[24:27], v113 offset:9344
	ds_read_b128 v[28:31], v113 offset:10400
	ds_read_b128 v[36:39], v113 offset:11424
	s_waitcnt lgkmcnt(7)
	v_mfma_f32_32x32x16_bf16 v[82:97], v[2:5], v[124:127], v[82:97]
	global_load_dwordx4 v[104:107], v[46:47], off
	v_mov_b32_e32 v2, 0
	v_mov_b32_e32 v3, v180
	v_mov_b32_e32 v4, v180
	v_mov_b32_e32 v5, v180
	v_readlane_b32 s11, v254, 63
	v_readlane_b32 s14, v255, 2
	s_waitcnt lgkmcnt(6)
	v_mfma_f32_32x32x16_bf16 v[66:81], v[6:9], v[124:127], v[66:81]
	v_mov_b32_e32 v6, v180
	v_mov_b32_e32 v7, v180
	v_mov_b32_e32 v8, v180
	v_mov_b32_e32 v9, v180
	v_readlane_b32 s15, v255, 3
	s_waitcnt lgkmcnt(5)
	v_mfma_f32_32x32x16_bf16 v[82:97], v[10:13], v[128:131], v[82:97]
	v_mov_b32_e32 v10, v180
	v_mov_b32_e32 v11, v180
	v_mov_b32_e32 v12, v180
	v_mov_b32_e32 v13, v180
	s_waitcnt lgkmcnt(4)
	v_mfma_f32_32x32x16_bf16 v[66:81], v[14:17], v[128:131], v[66:81]
	v_mov_b32_e32 v14, v180
	v_mov_b32_e32 v15, v180
	v_mov_b32_e32 v16, v180
	v_mov_b32_e32 v17, v180
	s_waitcnt lgkmcnt(3)
	v_mfma_f32_32x32x16_bf16 v[82:97], v[20:23], v[132:135], v[82:97]
	v_mov_b32_e32 v20, v180
	v_mov_b32_e32 v21, v180
	v_mov_b32_e32 v22, v180
	v_mov_b32_e32 v23, v180
	s_waitcnt lgkmcnt(2)
	v_mfma_f32_32x32x16_bf16 v[66:81], v[24:27], v[132:135], v[66:81]
	v_mov_b32_e32 v24, v180
	v_mov_b32_e32 v25, v180
	v_mov_b32_e32 v26, v180
	v_mov_b32_e32 v27, v180
	s_waitcnt lgkmcnt(1)
	v_mfma_f32_32x32x16_bf16 v[82:97], v[28:31], v[136:139], v[82:97]
	ds_read_b128 v[30:33], v113 offset:12480
	v_mov_b32_e32 v28, v180
	v_mov_b32_e32 v29, v180
	s_waitcnt lgkmcnt(1)
	v_mfma_f32_32x32x16_bf16 v[66:81], v[36:39], v[136:139], v[66:81]
	ds_read_b128 v[36:39], v113 offset:13504
	global_load_dwordx4 v[108:111], v[48:49], off
	global_load_dwordx4 v[164:167], v[40:41], off
	global_load_dwordx4 v[168:171], v[42:43], off
	global_load_dwordx4 v[194:197], v[44:45], off
	ds_read_b128 v[40:43], v113 offset:14560
	ds_read_b128 v[46:49], v113 offset:15584
	ds_read_b128 v[52:55], v113 offset:16640
	ds_read_b128 v[56:59], v177
	ds_read_b128 v[148:151], v113 offset:17664
	ds_read_b128 v[152:155], v177 offset:1024
	s_waitcnt lgkmcnt(7)
	v_mfma_f32_32x32x16_bf16 v[82:97], v[30:33], v[140:143], v[82:97]
	ds_read_b128 v[156:159], v113 offset:18720
	v_mov_b32_e32 v30, v180
	v_mov_b32_e32 v31, v180
	v_mov_b32_e32 v32, v180
	v_mov_b32_e32 v33, v180
	v_mov_b32_e32 v44, v180
	v_mov_b32_e32 v45, v180
	s_waitcnt lgkmcnt(7)
	v_mfma_f32_32x32x16_bf16 v[66:81], v[36:39], v[140:143], v[66:81]
	v_mov_b32_e32 v36, v180
	v_mov_b32_e32 v37, v180
	v_mov_b32_e32 v38, v180
	v_mov_b32_e32 v39, v180
	s_waitcnt lgkmcnt(6)
	v_mfma_f32_32x32x16_bf16 v[82:97], v[40:43], v[144:147], v[82:97]
	v_mov_b32_e32 v40, v180
	v_mov_b32_e32 v41, v180
	v_mov_b32_e32 v42, v180
	v_mov_b32_e32 v43, v180
	s_waitcnt lgkmcnt(5)
	v_mfma_f32_32x32x16_bf16 v[66:81], v[46:49], v[144:147], v[66:81]
	v_mov_b32_e32 v46, v180
	v_mov_b32_e32 v47, v180
	v_mov_b32_e32 v48, v180
	v_mov_b32_e32 v49, v180
	s_waitcnt lgkmcnt(3)
	v_mfma_f32_32x32x16_bf16 v[82:97], v[52:55], v[56:59], v[82:97]
	v_mov_b32_e32 v52, v180
	v_mov_b32_e32 v53, v180
	v_mov_b32_e32 v54, v180
	v_mov_b32_e32 v55, v180
	s_waitcnt lgkmcnt(2)
	v_mfma_f32_32x32x16_bf16 v[66:81], v[148:151], v[56:59], v[66:81]
	ds_read_b128 v[148:151], v113 offset:19744
	v_mov_b32_e32 v56, v180
	v_mov_b32_e32 v57, v180
	v_mov_b32_e32 v58, v180
	v_mov_b32_e32 v59, v180
	s_waitcnt lgkmcnt(1)
	v_mfma_f32_32x32x16_bf16 v[82:97], v[156:159], v[152:155], v[82:97]
	v_lshlrev_b32_e32 v156, 1, v175
	v_and_b32_e32 v161, 32, v156
	ds_read_b128 v[156:159], v113 offset:20800
	s_waitcnt lgkmcnt(1)
	v_mfma_f32_32x32x16_bf16 v[66:81], v[148:151], v[152:155], v[66:81]
	ds_read_b128 v[150:153], v177 offset:2048
	v_and_b32_e32 v148, 0x100, v160
	v_or3_b32 v112, v112, v161, v148
	v_add_u32_e32 v179, s1, v112
	s_addk_i32 s1, 0x4000
	ds_read_b128 v[198:201], v113 offset:21824
	ds_read_b128 v[202:205], v177 offset:3072
	v_add_u32_e32 v176, s1, v112
	s_add_u32 s1, s81, s82
	ds_read_b128 v[206:209], v113 offset:22880
	s_waitcnt lgkmcnt(3)
	v_mfma_f32_32x32x16_bf16 v[82:97], v[156:159], v[150:153], v[82:97]
	s_addc_u32 s3, s80, 0
	s_add_u32 s6, s12, s1
	s_addc_u32 s7, s13, s3
	v_lshl_add_u64 v[148:149], s[6:7], 0, v[98:99]
	v_lshl_add_u64 v[154:155], s[6:7], 0, v[100:101]
	v_lshl_add_u64 v[156:157], s[6:7], 0, v[102:103]
	s_waitcnt lgkmcnt(2)
	v_mfma_f32_32x32x16_bf16 v[66:81], v[198:201], v[150:153], v[66:81]
	v_lshl_add_u64 v[150:151], s[6:7], 0, v[64:65]
	v_lshl_add_u64 v[152:153], s[6:7], 0, v[62:63]
	ds_read_b128 v[62:65], v113 offset:23904
	s_waitcnt vmcnt(0)
	s_waitcnt vmcnt(4)
	ds_write_b128 v181, v[104:107] offset:16384
	s_waitcnt vmcnt(3)
	ds_write_b128 v182, v[108:111] offset:16384
	s_waitcnt vmcnt(2)
	ds_write_b128 v183, v[164:167] offset:57728
	s_waitcnt vmcnt(1)
	ds_write_b128 v192, v[168:171] offset:57728
	s_waitcnt vmcnt(0)
	ds_write_b128 v193, v[194:197] offset:57728
	s_waitcnt lgkmcnt(0)
	v_mfma_f32_32x32x16_bf16 v[82:97], v[206:209], v[202:205], v[82:97]
	s_barrier
	v_mfma_f32_32x32x16_bf16 v[66:81], v[62:65], v[202:205], v[66:81]
	s_nop 9
	v_exp_f32_e32 v197, v82
	v_exp_f32_e32 v199, v83
	v_exp_f32_e32 v195, v84
	v_exp_f32_e32 v198, v85
	v_exp_f32_e32 v194, v86
	v_exp_f32_e32 v196, v87
	v_exp_f32_e32 v170, v88
	v_exp_f32_e32 v171, v89
	v_exp_f32_e32 v167, v90
	v_exp_f32_e32 v169, v91
	v_exp_f32_e32 v166, v92
	v_exp_f32_e32 v168, v93
	v_exp_f32_e32 v158, v94
	v_exp_f32_e32 v165, v95
	v_exp_f32_e32 v159, v96
	v_exp_f32_e32 v164, v97
	v_mov_b32_e32 v62, v180
	v_mov_b32_e32 v63, v180
	v_mov_b32_e32 v64, v180
	v_mov_b32_e32 v65, v180
